# adds: nt cache hint on the f32 k/v output stores (never re-read by the kernel)
# baseline (speedup 1.0000x reference)
;     __device__ __forceinline__ void operator()(const f32x4 (&acc)[2][2][4][2], const pg8::Unit& u, int wr, int wc, int fr, int fq) const {
;     ...
;                     for (int bj = 0; bj < 2; ++bj) { u32x4 w;
; #pragma unroll
;                         for (int n = 0; n < 2; ++n) { const f32x4 v = acc[ai][bj][m][n] * sc; *(f32x4*)(fo + cb + bj * 128 + 4 * n) = v; w[2 * n] = pk2(v[0], v[1]); w[2 * n + 1] = pk2(v[2], v[3]); }
;                         *(u32x4*)(bo + cb + bj * 128) = w; } }
.LBB0_185:
	s_add_u32 s56, s22, s56
	s_addc_u32 s57, s23, s57
	v_lshlrev_b64 v[164:165], 10, v[164:165]
	v_ashrrev_i32_e32 v203, 31, v202
	v_lshl_add_u64 v[164:165], s[56:57], 0, v[164:165]
	v_lshl_add_u64 v[168:169], v[202:203], 2, v[162:163]
	v_lshl_add_u64 v[208:209], v[202:203], 1, v[164:165]
	s_waitcnt lgkmcnt(0)
	v_pk_mul_f32 v[162:163], v[158:159], v[200:201] op_sel_hi:[1,0]
	v_pk_mul_f32 v[164:165], v[160:161], v[200:201] op_sel_hi:[1,0]
	v_pk_mul_f32 v[204:205], v[154:155], v[200:201] op_sel_hi:[1,0]
	v_pk_mul_f32 v[206:207], v[156:157], v[200:201] op_sel_hi:[1,0]
	global_store_dwordx4 v[168:169], v[162:165], off nt
	global_store_dwordx4 v[168:169], v[204:207], off offset:16 nt
	s_and_b64 vcc, exec, s[42:43]
	v_cvt_pk_bf16_f32 v162, v162, v163
	v_cvt_pk_bf16_f32 v163, v164, v165
	v_cvt_pk_bf16_f32 v164, v204, v205
	v_cvt_pk_bf16_f32 v165, v206, v207
	global_store_dwordx4 v[208:209], v[162:165], off
	v_pk_mul_f32 v[204:205], v[146:147], v[200:201] op_sel_hi:[1,0]
	v_pk_mul_f32 v[206:207], v[148:149], v[200:201] op_sel_hi:[1,0]
	v_pk_mul_f32 v[162:163], v[150:151], v[200:201] op_sel_hi:[1,0]
	v_pk_mul_f32 v[164:165], v[152:153], v[200:201] op_sel_hi:[1,0]
	global_store_dwordx4 v[168:169], v[162:165], off offset:512 nt
	s_mov_b64 s[56:57], -1
	global_store_dwordx4 v[168:169], v[204:207], off offset:528 nt
	v_cvt_pk_bf16_f32 v162, v162, v163
	v_cvt_pk_bf16_f32 v163, v164, v165
	v_cvt_pk_bf16_f32 v164, v204, v205
	v_cvt_pk_bf16_f32 v165, v206, v207
	global_store_dwordx4 v[208:209], v[162:165], off offset:256
	s_cbranch_vccnz .LBB0_187
	s_nop 0
	v_add_u32_e32 v164, 16, v192
	v_ashrrev_i32_e32 v165, 31, v164
	s_add_u32 s56, s7, s10
	s_addc_u32 s57, s35, s11
	v_lshlrev_b64 v[162:163], 11, v[164:165]
	v_lshl_add_u64 v[162:163], s[56:57], 0, v[162:163]
	s_mov_b64 s[56:57], 0

;     __device__ __forceinline__ void operator()(const f32x4 (&acc)[2][2][4][2], const pg8::Unit& u, int wr, int wc, int fr, int fq) const {
;     ...
;                     for (int bj = 0; bj < 2; ++bj) { u32x4 w;
; #pragma unroll
;                         for (int n = 0; n < 2; ++n) { const f32x4 v = acc[ai][bj][m][n] * sc; *(f32x4*)(fo + cb + bj * 128 + 4 * n) = v; w[2 * n] = pk2(v[0], v[1]); w[2 * n + 1] = pk2(v[2], v[3]); }
;                         *(u32x4*)(bo + cb + bj * 128) = w; } }
.LBB0_189:
	s_add_u32 s56, s22, s56
	s_addc_u32 s57, s23, s57
	v_lshlrev_b64 v[164:165], 10, v[164:165]
	v_lshl_add_u64 v[164:165], s[56:57], 0, v[164:165]
	v_lshl_add_u64 v[168:169], v[202:203], 2, v[162:163]
	v_lshl_add_u64 v[208:209], v[202:203], 1, v[164:165]
	v_pk_mul_f32 v[162:163], v[142:143], v[200:201] op_sel:[0,1]
	v_pk_mul_f32 v[164:165], v[144:145], v[200:201] op_sel:[0,1]
	v_pk_mul_f32 v[204:205], v[138:139], v[200:201] op_sel:[0,1]
	v_pk_mul_f32 v[206:207], v[140:141], v[200:201] op_sel:[0,1]
	global_store_dwordx4 v[168:169], v[162:165], off nt
	global_store_dwordx4 v[168:169], v[204:207], off offset:16 nt
	s_and_b64 vcc, exec, s[42:43]
	v_cvt_pk_bf16_f32 v162, v162, v163
	v_cvt_pk_bf16_f32 v163, v164, v165
	v_cvt_pk_bf16_f32 v164, v204, v205
	v_cvt_pk_bf16_f32 v165, v206, v207
	global_store_dwordx4 v[208:209], v[162:165], off
	v_pk_mul_f32 v[204:205], v[130:131], v[200:201] op_sel:[0,1]
	v_pk_mul_f32 v[206:207], v[132:133], v[200:201] op_sel:[0,1]
	v_pk_mul_f32 v[162:163], v[134:135], v[200:201] op_sel:[0,1]
	v_pk_mul_f32 v[164:165], v[136:137], v[200:201] op_sel:[0,1]
	global_store_dwordx4 v[168:169], v[162:165], off offset:512 nt
	s_mov_b64 s[56:57], -1
	global_store_dwordx4 v[168:169], v[204:207], off offset:528 nt
	v_cvt_pk_bf16_f32 v162, v162, v163
	v_cvt_pk_bf16_f32 v163, v164, v165
	v_cvt_pk_bf16_f32 v164, v204, v205
	v_cvt_pk_bf16_f32 v165, v206, v207
	global_store_dwordx4 v[208:209], v[162:165], off offset:256
	s_cbranch_vccnz .LBB0_191
	s_nop 0
	v_add_u32_e32 v164, 32, v192
	v_ashrrev_i32_e32 v165, 31, v164
	s_add_u32 s56, s7, s10
	s_addc_u32 s57, s35, s11
	v_lshlrev_b64 v[162:163], 11, v[164:165]
	v_lshl_add_u64 v[162:163], s[56:57], 0, v[162:163]
	s_mov_b64 s[56:57], 0

;     __device__ __forceinline__ void operator()(const f32x4 (&acc)[2][2][4][2], const pg8::Unit& u, int wr, int wc, int fr, int fq) const {
;     ...
;                     for (int bj = 0; bj < 2; ++bj) { u32x4 w;
; #pragma unroll
;                         for (int n = 0; n < 2; ++n) { const f32x4 v = acc[ai][bj][m][n] * sc; *(f32x4*)(fo + cb + bj * 128 + 4 * n) = v; w[2 * n] = pk2(v[0], v[1]); w[2 * n + 1] = pk2(v[2], v[3]); }
;                         *(u32x4*)(bo + cb + bj * 128) = w; } }
.LBB0_193:
	s_add_u32 s56, s22, s56
	s_addc_u32 s57, s23, s57
	v_lshlrev_b64 v[164:165], 10, v[164:165]
	v_lshl_add_u64 v[164:165], s[56:57], 0, v[164:165]
	v_lshl_add_u64 v[208:209], v[202:203], 2, v[162:163]
	v_lshl_add_u64 v[210:211], v[202:203], 1, v[164:165]
	v_pk_mul_f32 v[162:163], v[126:127], v[198:199] op_sel_hi:[1,0]
	v_pk_mul_f32 v[164:165], v[128:129], v[198:199] op_sel_hi:[1,0]
	v_pk_mul_f32 v[204:205], v[122:123], v[198:199] op_sel_hi:[1,0]
	v_pk_mul_f32 v[206:207], v[124:125], v[198:199] op_sel_hi:[1,0]
	global_store_dwordx4 v[208:209], v[162:165], off nt
	global_store_dwordx4 v[208:209], v[204:207], off offset:16 nt
	s_and_b64 vcc, exec, s[42:43]
	v_cvt_pk_bf16_f32 v162, v162, v163
	v_cvt_pk_bf16_f32 v163, v164, v165
	v_cvt_pk_bf16_f32 v164, v204, v205
	v_cvt_pk_bf16_f32 v165, v206, v207
	global_store_dwordx4 v[210:211], v[162:165], off
	v_pk_mul_f32 v[204:205], v[114:115], v[198:199] op_sel_hi:[1,0]
	v_pk_mul_f32 v[206:207], v[116:117], v[198:199] op_sel_hi:[1,0]
	v_pk_mul_f32 v[162:163], v[118:119], v[198:199] op_sel_hi:[1,0]
	v_pk_mul_f32 v[164:165], v[120:121], v[198:199] op_sel_hi:[1,0]
	global_store_dwordx4 v[208:209], v[162:165], off offset:512 nt
	s_mov_b64 s[56:57], -1
	global_store_dwordx4 v[208:209], v[204:207], off offset:528 nt
	v_cvt_pk_bf16_f32 v162, v162, v163
	v_cvt_pk_bf16_f32 v163, v164, v165
	v_cvt_pk_bf16_f32 v164, v204, v205
	v_cvt_pk_bf16_f32 v165, v206, v207
	global_store_dwordx4 v[210:211], v[162:165], off offset:256
	s_cbranch_vccnz .LBB0_195
	s_nop 0
	v_add_u32_e32 v164, 48, v192
	v_ashrrev_i32_e32 v165, 31, v164
	s_add_u32 s56, s7, s10
	s_addc_u32 s57, s35, s11
	v_lshlrev_b64 v[162:163], 11, v[164:165]
	v_lshl_add_u64 v[162:163], s[56:57], 0, v[162:163]
	s_mov_b64 s[56:57], 0

;     __device__ __forceinline__ void operator()(const f32x4 (&acc)[2][2][4][2], const pg8::Unit& u, int wr, int wc, int fr, int fq) const {
;     ...
;                     for (int bj = 0; bj < 2; ++bj) { u32x4 w;
; #pragma unroll
;                         for (int n = 0; n < 2; ++n) { const f32x4 v = acc[ai][bj][m][n] * sc; *(f32x4*)(fo + cb + bj * 128 + 4 * n) = v; w[2 * n] = pk2(v[0], v[1]); w[2 * n + 1] = pk2(v[2], v[3]); }
;                         *(u32x4*)(bo + cb + bj * 128) = w; } }
.LBB0_197:
	s_add_u32 s56, s22, s56
	s_addc_u32 s57, s23, s57
	v_lshlrev_b64 v[164:165], 10, v[164:165]
	v_lshl_add_u64 v[164:165], s[56:57], 0, v[164:165]
	v_lshl_add_u64 v[208:209], v[202:203], 2, v[162:163]
	v_lshl_add_u64 v[210:211], v[202:203], 1, v[164:165]
	v_pk_mul_f32 v[162:163], v[106:107], v[198:199] op_sel:[0,1]
	v_pk_mul_f32 v[164:165], v[108:109], v[198:199] op_sel:[0,1]
	v_pk_mul_f32 v[204:205], v[86:87], v[198:199] op_sel:[0,1]
	v_pk_mul_f32 v[206:207], v[88:89], v[198:199] op_sel:[0,1]
	global_store_dwordx4 v[208:209], v[162:165], off nt
	global_store_dwordx4 v[208:209], v[204:207], off offset:16 nt
	s_and_b64 vcc, exec, s[42:43]
	v_cvt_pk_bf16_f32 v162, v162, v163
	v_cvt_pk_bf16_f32 v163, v164, v165
	v_cvt_pk_bf16_f32 v164, v204, v205
	v_cvt_pk_bf16_f32 v165, v206, v207
	global_store_dwordx4 v[210:211], v[162:165], off
	v_pk_mul_f32 v[204:205], v[66:67], v[198:199] op_sel:[0,1]
	v_pk_mul_f32 v[206:207], v[68:69], v[198:199] op_sel:[0,1]
	v_pk_mul_f32 v[162:163], v[70:71], v[198:199] op_sel:[0,1]
	v_pk_mul_f32 v[164:165], v[72:73], v[198:199] op_sel:[0,1]
	global_store_dwordx4 v[208:209], v[162:165], off offset:512 nt
	s_mov_b64 s[56:57], -1
	global_store_dwordx4 v[208:209], v[204:207], off offset:528 nt
	v_cvt_pk_bf16_f32 v162, v162, v163
	v_cvt_pk_bf16_f32 v163, v164, v165
	v_cvt_pk_bf16_f32 v164, v204, v205
	v_cvt_pk_bf16_f32 v165, v206, v207
	global_store_dwordx4 v[210:211], v[162:165], off offset:256
	s_cbranch_vccnz .LBB0_199
	s_nop 0
	v_add_u32_e32 v164, 0x80, v192
	v_ashrrev_i32_e32 v165, 31, v164
	s_add_u32 s56, s7, s10
	s_addc_u32 s57, s35, s11
	v_lshlrev_b64 v[162:163], 11, v[164:165]
	v_lshl_add_u64 v[162:163], s[56:57], 0, v[162:163]
	s_mov_b64 s[56:57], 0

;     __device__ __forceinline__ void operator()(const f32x4 (&acc)[2][2][4][2], const pg8::Unit& u, int wr, int wc, int fr, int fq) const {
;     ...
;                     for (int bj = 0; bj < 2; ++bj) { u32x4 w;
; #pragma unroll
;                         for (int n = 0; n < 2; ++n) { const f32x4 v = acc[ai][bj][m][n] * sc; *(f32x4*)(fo + cb + bj * 128 + 4 * n) = v; w[2 * n] = pk2(v[0], v[1]); w[2 * n + 1] = pk2(v[2], v[3]); }
;                         *(u32x4*)(bo + cb + bj * 128) = w; } }
.LBB0_201:
	s_add_u32 s56, s22, s56
	s_addc_u32 s57, s23, s57
	v_lshlrev_b64 v[164:165], 10, v[164:165]
	v_lshl_add_u64 v[164:165], s[56:57], 0, v[164:165]
	v_lshl_add_u64 v[208:209], v[202:203], 2, v[162:163]
	v_lshl_add_u64 v[210:211], v[202:203], 1, v[164:165]
	v_pk_mul_f32 v[162:163], v[62:63], v[196:197] op_sel_hi:[1,0]
	v_pk_mul_f32 v[164:165], v[64:65], v[196:197] op_sel_hi:[1,0]
	v_pk_mul_f32 v[204:205], v[58:59], v[196:197] op_sel_hi:[1,0]
	v_pk_mul_f32 v[206:207], v[60:61], v[196:197] op_sel_hi:[1,0]
	global_store_dwordx4 v[208:209], v[162:165], off nt
	global_store_dwordx4 v[208:209], v[204:207], off offset:16 nt
	s_and_b64 vcc, exec, s[42:43]
	v_cvt_pk_bf16_f32 v162, v162, v163
	v_cvt_pk_bf16_f32 v163, v164, v165
	v_cvt_pk_bf16_f32 v164, v204, v205
	v_cvt_pk_bf16_f32 v165, v206, v207
	global_store_dwordx4 v[210:211], v[162:165], off
	v_pk_mul_f32 v[204:205], v[50:51], v[196:197] op_sel_hi:[1,0]
	v_pk_mul_f32 v[206:207], v[52:53], v[196:197] op_sel_hi:[1,0]
	v_pk_mul_f32 v[162:163], v[54:55], v[196:197] op_sel_hi:[1,0]
	v_pk_mul_f32 v[164:165], v[56:57], v[196:197] op_sel_hi:[1,0]
	global_store_dwordx4 v[208:209], v[162:165], off offset:512 nt
	s_mov_b64 s[56:57], -1
	global_store_dwordx4 v[208:209], v[204:207], off offset:528 nt
	v_cvt_pk_bf16_f32 v162, v162, v163
	v_cvt_pk_bf16_f32 v163, v164, v165
	v_cvt_pk_bf16_f32 v164, v204, v205
	v_cvt_pk_bf16_f32 v165, v206, v207
	global_store_dwordx4 v[210:211], v[162:165], off offset:256
	s_cbranch_vccnz .LBB0_203
	s_nop 0
	v_add_u32_e32 v164, 0x90, v192
	v_ashrrev_i32_e32 v165, 31, v164
	s_add_u32 s56, s7, s10
	s_addc_u32 s57, s35, s11
	v_lshlrev_b64 v[162:163], 11, v[164:165]
	v_lshl_add_u64 v[162:163], s[56:57], 0, v[162:163]
	s_mov_b64 s[56:57], 0

;     __device__ __forceinline__ void operator()(const f32x4 (&acc)[2][2][4][2], const pg8::Unit& u, int wr, int wc, int fr, int fq) const {
;     ...
;                     for (int bj = 0; bj < 2; ++bj) { u32x4 w;
; #pragma unroll
;                         for (int n = 0; n < 2; ++n) { const f32x4 v = acc[ai][bj][m][n] * sc; *(f32x4*)(fo + cb + bj * 128 + 4 * n) = v; w[2 * n] = pk2(v[0], v[1]); w[2 * n + 1] = pk2(v[2], v[3]); }
;                         *(u32x4*)(bo + cb + bj * 128) = w; } }
.LBB0_205:
	s_add_u32 s56, s22, s56
	s_addc_u32 s57, s23, s57
	v_lshlrev_b64 v[164:165], 10, v[164:165]
	v_lshl_add_u64 v[164:165], s[56:57], 0, v[164:165]
	v_lshl_add_u64 v[204:205], v[202:203], 2, v[162:163]
	v_lshl_add_u64 v[206:207], v[202:203], 1, v[164:165]
	v_pk_mul_f32 v[162:163], v[46:47], v[196:197] op_sel:[0,1]
	v_pk_mul_f32 v[164:165], v[48:49], v[196:197] op_sel:[0,1]
	global_store_dwordx4 v[204:205], v[162:165], off nt
	v_pk_mul_f32 v[166:167], v[44:45], v[196:197] op_sel:[0,1]
	s_and_b64 vcc, exec, s[42:43]
	v_cvt_pk_bf16_f32 v162, v162, v163
	v_cvt_pk_bf16_f32 v163, v164, v165
	v_pk_mul_f32 v[164:165], v[42:43], v[196:197] op_sel:[0,1]
	global_store_dwordx4 v[204:205], v[164:167], off offset:16 nt
	s_mov_b64 s[56:57], -1
	s_nop 0
	v_cvt_pk_bf16_f32 v164, v164, v165
	v_cvt_pk_bf16_f32 v165, v166, v167
	global_store_dwordx4 v[206:207], v[162:165], off
	v_pk_mul_f32 v[166:167], v[36:37], v[196:197] op_sel:[0,1]
	s_nop 0
	v_pk_mul_f32 v[162:163], v[38:39], v[196:197] op_sel:[0,1]
	v_pk_mul_f32 v[164:165], v[40:41], v[196:197] op_sel:[0,1]
	global_store_dwordx4 v[204:205], v[162:165], off offset:512 nt
	s_nop 1
	v_cvt_pk_bf16_f32 v162, v162, v163
	v_cvt_pk_bf16_f32 v163, v164, v165
	v_pk_mul_f32 v[164:165], v[34:35], v[196:197] op_sel:[0,1]
	global_store_dwordx4 v[204:205], v[164:167], off offset:528 nt
	s_nop 1
	v_cvt_pk_bf16_f32 v164, v164, v165
	v_cvt_pk_bf16_f32 v165, v166, v167
	global_store_dwordx4 v[206:207], v[162:165], off offset:256
	s_cbranch_vccnz .LBB0_207
	s_nop 0
	v_add_u32_e32 v164, 0xa0, v192
	v_ashrrev_i32_e32 v165, 31, v164
	s_add_u32 s56, s7, s10
	s_addc_u32 s57, s35, s11
	v_lshlrev_b64 v[162:163], 11, v[164:165]
	v_lshl_add_u64 v[162:163], s[56:57], 0, v[162:163]
	s_mov_b64 s[56:57], 0

;     __device__ __forceinline__ void operator()(const f32x4 (&acc)[2][2][4][2], const pg8::Unit& u, int wr, int wc, int fr, int fq) const {
;     ...
;                     for (int bj = 0; bj < 2; ++bj) { u32x4 w;
; #pragma unroll
;                         for (int n = 0; n < 2; ++n) { const f32x4 v = acc[ai][bj][m][n] * sc; *(f32x4*)(fo + cb + bj * 128 + 4 * n) = v; w[2 * n] = pk2(v[0], v[1]); w[2 * n + 1] = pk2(v[2], v[3]); }
;                         *(u32x4*)(bo + cb + bj * 128) = w; } }
.LBB0_209:
	s_add_u32 s56, s22, s56
	s_addc_u32 s57, s23, s57
	v_lshlrev_b64 v[164:165], 10, v[164:165]
	v_lshl_add_u64 v[164:165], s[56:57], 0, v[164:165]
	v_lshl_add_u64 v[204:205], v[202:203], 2, v[162:163]
	v_lshl_add_u64 v[206:207], v[202:203], 1, v[164:165]
	v_pk_mul_f32 v[162:163], v[30:31], v[194:195] op_sel_hi:[1,0]
	v_pk_mul_f32 v[164:165], v[32:33], v[194:195] op_sel_hi:[1,0]
	global_store_dwordx4 v[204:205], v[162:165], off nt
	v_pk_mul_f32 v[166:167], v[28:29], v[194:195] op_sel_hi:[1,0]
	s_and_b64 vcc, exec, s[42:43]
	v_cvt_pk_bf16_f32 v162, v162, v163
	v_cvt_pk_bf16_f32 v163, v164, v165
	v_pk_mul_f32 v[164:165], v[26:27], v[194:195] op_sel_hi:[1,0]
	global_store_dwordx4 v[204:205], v[164:167], off offset:16 nt
	s_mov_b64 s[42:43], -1
	s_nop 0
	v_cvt_pk_bf16_f32 v164, v164, v165
	v_cvt_pk_bf16_f32 v165, v166, v167
	global_store_dwordx4 v[206:207], v[162:165], off
	v_pk_mul_f32 v[166:167], v[20:21], v[194:195] op_sel_hi:[1,0]
	s_nop 0
	v_pk_mul_f32 v[162:163], v[22:23], v[194:195] op_sel_hi:[1,0]
	v_pk_mul_f32 v[164:165], v[24:25], v[194:195] op_sel_hi:[1,0]
	global_store_dwordx4 v[204:205], v[162:165], off offset:512 nt
	s_nop 1
	v_cvt_pk_bf16_f32 v162, v162, v163
	v_cvt_pk_bf16_f32 v163, v164, v165
	v_pk_mul_f32 v[164:165], v[18:19], v[194:195] op_sel_hi:[1,0]
	global_store_dwordx4 v[204:205], v[164:167], off offset:528 nt
	s_nop 1
	v_cvt_pk_bf16_f32 v164, v164, v165
	v_cvt_pk_bf16_f32 v165, v166, v167
	global_store_dwordx4 v[206:207], v[162:165], off offset:256
	s_cbranch_vccnz .LBB0_211
	s_nop 0
	v_add_u32_e32 v164, 0xb0, v192
	v_ashrrev_i32_e32 v165, 31, v164
	s_add_u32 s34, s7, s10
	s_addc_u32 s35, s35, s11
	v_lshlrev_b64 v[162:163], 11, v[164:165]
	v_lshl_add_u64 v[162:163], s[34:35], 0, v[162:163]
	s_mov_b64 s[42:43], 0

;     __device__ __forceinline__ void operator()(const f32x4 (&acc)[2][2][4][2], const pg8::Unit& u, int wr, int wc, int fr, int fq) const {
;     ...
;                     for (int bj = 0; bj < 2; ++bj) { u32x4 w;
; #pragma unroll
;                         for (int n = 0; n < 2; ++n) { const f32x4 v = acc[ai][bj][m][n] * sc; *(f32x4*)(fo + cb + bj * 128 + 4 * n) = v; w[2 * n] = pk2(v[0], v[1]); w[2 * n + 1] = pk2(v[2], v[3]); }
;                         *(u32x4*)(bo + cb + bj * 128) = w; } }
.LBB0_213:
	s_add_u32 s6, s22, s42
	s_addc_u32 s7, s23, s43
	v_lshlrev_b64 v[164:165], 10, v[164:165]
	v_lshl_add_u64 v[164:165], s[6:7], 0, v[164:165]
	v_lshl_add_u64 v[168:169], v[202:203], 2, v[162:163]
	v_lshl_add_u64 v[204:205], v[202:203], 1, v[164:165]
	v_pk_mul_f32 v[162:163], v[14:15], v[194:195] op_sel:[0,1]
	v_pk_mul_f32 v[164:165], v[16:17], v[194:195] op_sel:[0,1]
	global_store_dwordx4 v[168:169], v[162:165], off nt
	v_pk_mul_f32 v[166:167], v[12:13], v[194:195] op_sel:[0,1]
	s_nop 0
	v_cvt_pk_bf16_f32 v162, v162, v163
	v_cvt_pk_bf16_f32 v163, v164, v165
	v_pk_mul_f32 v[164:165], v[10:11], v[194:195] op_sel:[0,1]
	global_store_dwordx4 v[168:169], v[164:167], off offset:16 nt
	s_nop 1
	v_cvt_pk_bf16_f32 v164, v164, v165
	v_cvt_pk_bf16_f32 v165, v166, v167
	global_store_dwordx4 v[204:205], v[162:165], off
	v_pk_mul_f32 v[166:167], v[4:5], v[194:195] op_sel:[0,1]
	s_nop 0
	v_pk_mul_f32 v[162:163], v[6:7], v[194:195] op_sel:[0,1]
	v_pk_mul_f32 v[164:165], v[8:9], v[194:195] op_sel:[0,1]
	global_store_dwordx4 v[168:169], v[162:165], off offset:512 nt
	s_nop 1
	v_cvt_pk_bf16_f32 v162, v162, v163
	v_cvt_pk_bf16_f32 v163, v164, v165
	v_pk_mul_f32 v[164:165], v[2:3], v[194:195] op_sel:[0,1]
	global_store_dwordx4 v[168:169], v[164:167], off offset:528 nt
	s_nop 1
	v_cvt_pk_bf16_f32 v164, v164, v165
	v_cvt_pk_bf16_f32 v165, v166, v167
	global_store_dwordx4 v[204:205], v[162:165], off offset:256
	s_waitcnt vmcnt(48)
